# code placement: the nine GEMM K-loop heads aligned to 64 bytes (.p2align 6), otherwise identical to the P2b-ring version
# speedup vs baseline: 1.0025x; 1.0025x over previous
.LBB0_131:
	s_mov_b32 s69, 32
	s_cmp_lt_i32 s69, 1
	s_cbranch_scc1 .LBB0_134
	s_add_i32 s70, s69, -2
	s_add_u32 s4, s4, 0x80080
	s_addc_u32 s5, s5, 0
	s_add_u32 s71, s46, 0x100
	v_mov_b32_e32 v0, 0
	s_addc_u32 s72, s47, 0
	s_mov_b32 s46, 0
	v_mov_b32_e32 v1, v0
	v_mov_b32_e32 v2, v0
	v_mov_b32_e32 v3, v0
	v_mov_b32_e32 v4, v0
	v_mov_b32_e32 v5, v0
	v_mov_b32_e32 v6, v0
	v_mov_b32_e32 v7, v0
	v_mov_b32_e32 v16, v0
	v_mov_b32_e32 v17, v0
	v_mov_b32_e32 v18, v0
	v_mov_b32_e32 v19, v0
	v_mov_b32_e32 v20, v0
	v_mov_b32_e32 v21, v0
	v_mov_b32_e32 v22, v0
	v_mov_b32_e32 v23, v0
	v_mov_b32_e32 v32, v0
	v_mov_b32_e32 v33, v0
	v_mov_b32_e32 v34, v0
	v_mov_b32_e32 v35, v0
	v_mov_b32_e32 v36, v0
	v_mov_b32_e32 v37, v0
	v_mov_b32_e32 v38, v0
	v_mov_b32_e32 v39, v0
	v_mov_b32_e32 v48, v0
	v_mov_b32_e32 v49, v0
	v_mov_b32_e32 v50, v0
	v_mov_b32_e32 v51, v0
	v_mov_b32_e32 v52, v0
	v_mov_b32_e32 v53, v0
	v_mov_b32_e32 v54, v0
	v_mov_b32_e32 v55, v0
	v_mov_b32_e32 v12, v0
	v_mov_b32_e32 v13, v0
	v_mov_b32_e32 v14, v0
	v_mov_b32_e32 v15, v0
	v_mov_b32_e32 v8, v0
	v_mov_b32_e32 v9, v0
	v_mov_b32_e32 v10, v0
	v_mov_b32_e32 v11, v0
	v_mov_b32_e32 v28, v0
	v_mov_b32_e32 v29, v0
	v_mov_b32_e32 v30, v0
	v_mov_b32_e32 v31, v0
	v_mov_b32_e32 v24, v0
	v_mov_b32_e32 v25, v0
	v_mov_b32_e32 v26, v0
	v_mov_b32_e32 v27, v0
	v_mov_b32_e32 v44, v0
	v_mov_b32_e32 v45, v0
	v_mov_b32_e32 v46, v0
	v_mov_b32_e32 v47, v0
	v_mov_b32_e32 v40, v0
	v_mov_b32_e32 v41, v0
	v_mov_b32_e32 v42, v0
	v_mov_b32_e32 v43, v0
	v_mov_b32_e32 v60, v0
	v_mov_b32_e32 v61, v0
	v_mov_b32_e32 v62, v0
	v_mov_b32_e32 v63, v0
	v_mov_b32_e32 v56, v0
	v_mov_b32_e32 v57, v0
	v_mov_b32_e32 v58, v0
	v_mov_b32_e32 v59, v0
	v_mov_b32_e32 v64, v0
	v_mov_b32_e32 v65, v0
	v_mov_b32_e32 v66, v0
	v_mov_b32_e32 v67, v0
	v_mov_b32_e32 v68, v0
	v_mov_b32_e32 v69, v0
	v_mov_b32_e32 v70, v0
	v_mov_b32_e32 v71, v0
	v_mov_b32_e32 v80, v0
	v_mov_b32_e32 v81, v0
	v_mov_b32_e32 v82, v0
	v_mov_b32_e32 v83, v0
	v_mov_b32_e32 v84, v0
	v_mov_b32_e32 v85, v0
	v_mov_b32_e32 v86, v0
	v_mov_b32_e32 v87, v0
	v_mov_b32_e32 v96, v0
	v_mov_b32_e32 v97, v0
	v_mov_b32_e32 v98, v0
	v_mov_b32_e32 v99, v0
	v_mov_b32_e32 v100, v0
	v_mov_b32_e32 v101, v0
	v_mov_b32_e32 v102, v0
	v_mov_b32_e32 v103, v0
	v_mov_b32_e32 v112, v0
	v_mov_b32_e32 v113, v0
	v_mov_b32_e32 v114, v0
	v_mov_b32_e32 v115, v0
	v_mov_b32_e32 v116, v0
	v_mov_b32_e32 v117, v0
	v_mov_b32_e32 v118, v0
	v_mov_b32_e32 v119, v0
	v_mov_b32_e32 v76, v0
	v_mov_b32_e32 v77, v0
	v_mov_b32_e32 v78, v0
	v_mov_b32_e32 v79, v0
	v_mov_b32_e32 v72, v0
	v_mov_b32_e32 v73, v0
	v_mov_b32_e32 v74, v0
	v_mov_b32_e32 v75, v0
	v_mov_b32_e32 v92, v0
	v_mov_b32_e32 v93, v0
	v_mov_b32_e32 v94, v0
	v_mov_b32_e32 v95, v0
	v_mov_b32_e32 v88, v0
	v_mov_b32_e32 v89, v0
	v_mov_b32_e32 v90, v0
	v_mov_b32_e32 v91, v0
	v_mov_b32_e32 v108, v0
	v_mov_b32_e32 v109, v0
	v_mov_b32_e32 v110, v0
	v_mov_b32_e32 v111, v0
	v_mov_b32_e32 v104, v0
	v_mov_b32_e32 v105, v0
	v_mov_b32_e32 v106, v0
	v_mov_b32_e32 v107, v0
	v_mov_b32_e32 v124, v0
	v_mov_b32_e32 v125, v0
	v_mov_b32_e32 v126, v0
	v_mov_b32_e32 v127, v0
	v_mov_b32_e32 v120, v0
	v_mov_b32_e32 v121, v0
	v_mov_b32_e32 v122, v0
	v_mov_b32_e32 v123, v0
	.p2align	6

.LBB0_360:
	s_mov_b32 s82, 2
	s_cmp_lt_i32 s82, 1
	s_cbranch_scc1 .LBB0_376
	s_add_i32 s83, s82, -2
	s_add_u32 s84, s50, 0x100
	s_addc_u32 s85, s51, 0
	s_add_u32 s48, s48, 0x8080
	v_mov_b32_e32 v64, 0
	s_addc_u32 s49, s49, 0
	s_mov_b32 s50, 0
	v_mov_b32_e32 v65, v64
	v_mov_b32_e32 v66, v64
	v_mov_b32_e32 v67, v64
	v_mov_b32_e32 v68, v64
	v_mov_b32_e32 v69, v64
	v_mov_b32_e32 v70, v64
	v_mov_b32_e32 v71, v64
	v_mov_b32_e32 v80, v64
	v_mov_b32_e32 v81, v64
	v_mov_b32_e32 v82, v64
	v_mov_b32_e32 v83, v64
	v_mov_b32_e32 v84, v64
	v_mov_b32_e32 v85, v64
	v_mov_b32_e32 v86, v64
	v_mov_b32_e32 v87, v64
	v_mov_b32_e32 v96, v64
	v_mov_b32_e32 v97, v64
	v_mov_b32_e32 v98, v64
	v_mov_b32_e32 v99, v64
	v_mov_b32_e32 v100, v64
	v_mov_b32_e32 v101, v64
	v_mov_b32_e32 v102, v64
	v_mov_b32_e32 v103, v64
	v_mov_b32_e32 v112, v64
	v_mov_b32_e32 v113, v64
	v_mov_b32_e32 v114, v64
	v_mov_b32_e32 v115, v64
	v_mov_b32_e32 v116, v64
	v_mov_b32_e32 v117, v64
	v_mov_b32_e32 v118, v64
	v_mov_b32_e32 v119, v64
	v_mov_b32_e32 v72, v64
	v_mov_b32_e32 v73, v64
	v_mov_b32_e32 v74, v64
	v_mov_b32_e32 v75, v64
	v_mov_b32_e32 v76, v64
	v_mov_b32_e32 v77, v64
	v_mov_b32_e32 v78, v64
	v_mov_b32_e32 v79, v64
	v_mov_b32_e32 v88, v64
	v_mov_b32_e32 v89, v64
	v_mov_b32_e32 v90, v64
	v_mov_b32_e32 v91, v64
	v_mov_b32_e32 v92, v64
	v_mov_b32_e32 v93, v64
	v_mov_b32_e32 v94, v64
	v_mov_b32_e32 v95, v64
	v_mov_b32_e32 v104, v64
	v_mov_b32_e32 v105, v64
	v_mov_b32_e32 v106, v64
	v_mov_b32_e32 v107, v64
	v_mov_b32_e32 v108, v64
	v_mov_b32_e32 v109, v64
	v_mov_b32_e32 v110, v64
	v_mov_b32_e32 v111, v64
	v_mov_b32_e32 v120, v64
	v_mov_b32_e32 v121, v64
	v_mov_b32_e32 v122, v64
	v_mov_b32_e32 v123, v64
	v_mov_b32_e32 v124, v64
	v_mov_b32_e32 v125, v64
	v_mov_b32_e32 v126, v64
	v_mov_b32_e32 v127, v64
	v_mov_b32_e32 v0, v64
	v_mov_b32_e32 v1, v64
	v_mov_b32_e32 v2, v64
	v_mov_b32_e32 v3, v64
	v_mov_b32_e32 v4, v64
	v_mov_b32_e32 v5, v64
	v_mov_b32_e32 v6, v64
	v_mov_b32_e32 v7, v64
	v_mov_b32_e32 v16, v64
	v_mov_b32_e32 v17, v64
	v_mov_b32_e32 v18, v64
	v_mov_b32_e32 v19, v64
	v_mov_b32_e32 v20, v64
	v_mov_b32_e32 v21, v64
	v_mov_b32_e32 v22, v64
	v_mov_b32_e32 v23, v64
	v_mov_b32_e32 v32, v64
	v_mov_b32_e32 v33, v64
	v_mov_b32_e32 v34, v64
	v_mov_b32_e32 v35, v64
	v_mov_b32_e32 v36, v64
	v_mov_b32_e32 v37, v64
	v_mov_b32_e32 v38, v64
	v_mov_b32_e32 v39, v64
	v_mov_b32_e32 v48, v64
	v_mov_b32_e32 v49, v64
	v_mov_b32_e32 v50, v64
	v_mov_b32_e32 v51, v64
	v_mov_b32_e32 v52, v64
	v_mov_b32_e32 v53, v64
	v_mov_b32_e32 v54, v64
	v_mov_b32_e32 v55, v64
	v_mov_b32_e32 v8, v64
	v_mov_b32_e32 v9, v64
	v_mov_b32_e32 v10, v64
	v_mov_b32_e32 v11, v64
	v_mov_b32_e32 v12, v64
	v_mov_b32_e32 v13, v64
	v_mov_b32_e32 v14, v64
	v_mov_b32_e32 v15, v64
	v_mov_b32_e32 v24, v64
	v_mov_b32_e32 v25, v64
	v_mov_b32_e32 v26, v64
	v_mov_b32_e32 v27, v64
	v_mov_b32_e32 v28, v64
	v_mov_b32_e32 v29, v64
	v_mov_b32_e32 v30, v64
	v_mov_b32_e32 v31, v64
	v_mov_b32_e32 v40, v64
	v_mov_b32_e32 v41, v64
	v_mov_b32_e32 v42, v64
	v_mov_b32_e32 v43, v64
	v_mov_b32_e32 v44, v64
	v_mov_b32_e32 v45, v64
	v_mov_b32_e32 v46, v64
	v_mov_b32_e32 v47, v64
	v_mov_b32_e32 v56, v64
	v_mov_b32_e32 v57, v64
	v_mov_b32_e32 v58, v64
	v_mov_b32_e32 v59, v64
	v_mov_b32_e32 v60, v64
	v_mov_b32_e32 v61, v64
	v_mov_b32_e32 v62, v64
	v_mov_b32_e32 v63, v64
	.p2align	6

.LBB0_442:
	v_mov_b32_e32 v128, v155
	v_mov_b32_e32 v130, v156
	s_nop 0
	v_add_u32_e32 v131, s92, v128
	v_mov_b64_e32 v[128:129], s[8:9]
	v_mad_i64_i32 v[128:129], s[40:41], v131, s70, v[128:129]
	v_lshl_add_u64 v[128:129], s[52:53], 1, v[128:129]
	v_lshlrev_b32_e32 v130, 3, v130
	v_lshl_add_u64 v[128:129], v[128:129], 0, s[4:5]
	v_ashrrev_i32_e32 v131, 31, v130
	v_lshl_add_u64 v[152:153], v[130:131], 1, v[128:129]
	v_add_co_u32_e32 v128, vcc, 0x2000, v152
	s_nop 1
	v_addc_co_u32_e32 v129, vcc, 0, v153, vcc
	flat_load_dwordx4 v[160:163], v[128:129] offset:2048
	v_lshl_add_u64 v[128:129], v[152:153], 0, s[42:43]
	flat_load_dwordx4 v[166:169], v[128:129] offset:512
	v_add_co_u32_e32 v128, vcc, 0x4a000, v152
	s_waitcnt vmcnt(0) lgkmcnt(0)
	v_lshlrev_b32_e32 v188, 16, v160
	v_addc_co_u32_e32 v129, vcc, 0, v153, vcc
	flat_load_dwordx4 v[170:173], v[128:129] offset:2048
	flat_load_dwordx4 v[136:139], v[128:129] offset:2560
	v_add_co_u32_e32 v128, vcc, 0x92000, v152
	v_and_b32_e32 v189, 0xffff0000, v160
	s_nop 0
	v_addc_co_u32_e32 v129, vcc, 0, v153, vcc
	flat_load_dwordx4 v[132:135], v[128:129] offset:2048
	s_nop 0
	flat_load_dwordx4 v[128:131], v[128:129] offset:2560
	v_add_co_u32_e32 v186, vcc, s74, v152
	v_lshlrev_b32_e32 v160, 16, v161
	s_nop 0
	v_addc_co_u32_e32 v187, vcc, 0, v153, vcc
	v_add_co_u32_e32 v178, vcc, 0xda000, v152
	v_and_b32_e32 v161, 0xffff0000, v161
	s_nop 0
	v_addc_co_u32_e32 v179, vcc, 0, v153, vcc
	flat_load_dwordx4 v[174:177], v[178:179] offset:2048
	s_nop 0
	flat_load_dwordx4 v[178:181], v[178:179] offset:2560
	flat_load_dwordx4 v[182:185], v[186:187] offset:2048
	v_lshlrev_b32_e32 v192, 16, v166
	v_and_b32_e32 v193, 0xffff0000, v166
	v_lshlrev_b32_e32 v166, 16, v167
	v_and_b32_e32 v167, 0xffff0000, v167
	v_pk_mul_f32 v[126:127], v[126:127], v[160:161]
	v_lshlrev_b32_e32 v190, 16, v162
	v_and_b32_e32 v191, 0xffff0000, v162
	v_lshlrev_b32_e32 v162, 16, v163
	v_and_b32_e32 v163, 0xffff0000, v163
	v_lshlrev_b32_e32 v194, 16, v168
	v_and_b32_e32 v195, 0xffff0000, v168
	v_lshlrev_b32_e32 v168, 16, v169
	v_and_b32_e32 v169, 0xffff0000, v169
	v_pk_mul_f32 v[118:119], v[118:119], v[166:167]
	v_pk_mul_f32 v[122:123], v[122:123], v[162:163]
	v_pk_mul_f32 v[114:115], v[114:115], v[168:169]
	v_pk_mul_f32 v[124:125], v[124:125], v[188:189]
	v_pk_mul_f32 v[120:121], v[120:121], v[190:191]
	v_pk_mul_f32 v[116:117], v[116:117], v[192:193]
	v_pk_mul_f32 v[112:113], v[112:113], v[194:195]
	s_waitcnt vmcnt(0) lgkmcnt(0)
	v_lshlrev_b32_e32 v160, 16, v170
	v_and_b32_e32 v161, 0xffff0000, v170
	v_lshlrev_b32_e32 v166, 16, v171
	v_and_b32_e32 v167, 0xffff0000, v171
	v_lshlrev_b32_e32 v170, 16, v136
	v_and_b32_e32 v171, 0xffff0000, v136
	v_lshlrev_b32_e32 v136, 16, v137
	v_and_b32_e32 v137, 0xffff0000, v137
	v_pk_mul_f32 v[108:109], v[108:109], v[160:161]
	v_lshlrev_b32_e32 v160, 16, v139
	v_and_b32_e32 v161, 0xffff0000, v139
	v_lshlrev_b32_e32 v162, 16, v172
	v_and_b32_e32 v163, 0xffff0000, v172
	v_lshlrev_b32_e32 v168, 16, v173
	v_and_b32_e32 v169, 0xffff0000, v173
	v_lshlrev_b32_e32 v172, 16, v138
	v_and_b32_e32 v173, 0xffff0000, v138
	v_pk_mul_f32 v[110:111], v[110:111], v[166:167]
	v_pk_mul_f32 v[102:103], v[102:103], v[136:137]
	flat_load_dwordx4 v[136:139], v[186:187] offset:2560
	v_pk_mul_f32 v[98:99], v[98:99], v[160:161]
	v_lshlrev_b32_e32 v160, 16, v132
	v_and_b32_e32 v161, 0xffff0000, v132
	v_add_co_u32_e32 v166, vcc, s75, v152
	v_pk_mul_f32 v[92:93], v[92:93], v[160:161]
	v_lshlrev_b32_e32 v160, 16, v134
	v_and_b32_e32 v161, 0xffff0000, v134
	v_addc_co_u32_e32 v167, vcc, 0, v153, vcc
	v_pk_mul_f32 v[104:105], v[104:105], v[162:163]
	v_pk_mul_f32 v[88:89], v[88:89], v[160:161]
	flat_load_dwordx4 v[160:163], v[166:167] offset:2048
	v_lshlrev_b32_e32 v132, 16, v133
	v_and_b32_e32 v133, 0xffff0000, v133
	v_pk_mul_f32 v[94:95], v[94:95], v[132:133]
	v_lshlrev_b32_e32 v132, 16, v135
	v_and_b32_e32 v133, 0xffff0000, v135
	v_pk_mul_f32 v[90:91], v[90:91], v[132:133]
	v_lshlrev_b32_e32 v132, 16, v128
	v_and_b32_e32 v133, 0xffff0000, v128
	v_pk_mul_f32 v[106:107], v[106:107], v[168:169]
	v_pk_mul_f32 v[84:85], v[84:85], v[132:133]
	v_lshlrev_b32_e32 v168, 16, v130
	v_and_b32_e32 v169, 0xffff0000, v130
	flat_load_dwordx4 v[132:135], v[166:167] offset:2560
	v_lshlrev_b32_e32 v128, 16, v129
	v_and_b32_e32 v129, 0xffff0000, v129
	v_add_co_u32_e32 v166, vcc, s76, v152
	v_pk_mul_f32 v[80:81], v[80:81], v[168:169]
	v_pk_mul_f32 v[86:87], v[86:87], v[128:129]
	v_lshlrev_b32_e32 v128, 16, v131
	v_and_b32_e32 v129, 0xffff0000, v131
	v_addc_co_u32_e32 v167, vcc, 0, v153, vcc
	v_lshlrev_b32_e32 v168, 16, v174
	v_and_b32_e32 v169, 0xffff0000, v174
	v_pk_mul_f32 v[82:83], v[82:83], v[128:129]
	flat_load_dwordx4 v[128:131], v[166:167] offset:2048
	v_pk_mul_f32 v[76:77], v[76:77], v[168:169]
	v_lshlrev_b32_e32 v168, 16, v176
	v_and_b32_e32 v169, 0xffff0000, v176
	v_pk_mul_f32 v[72:73], v[72:73], v[168:169]
	v_lshlrev_b32_e32 v168, 16, v175
	v_and_b32_e32 v169, 0xffff0000, v175
	v_pk_mul_f32 v[78:79], v[78:79], v[168:169]
	flat_load_dwordx4 v[166:169], v[166:167] offset:2560
	v_pk_mul_f32 v[100:101], v[100:101], v[170:171]
	v_lshlrev_b32_e32 v170, 16, v177
	v_and_b32_e32 v171, 0xffff0000, v177
	v_pk_mul_f32 v[74:75], v[74:75], v[170:171]
	v_lshlrev_b32_e32 v170, 16, v178
	v_and_b32_e32 v171, 0xffff0000, v178
	v_add_co_u32_e32 v152, vcc, s79, v152
	v_pk_mul_f32 v[68:69], v[68:69], v[170:171]
	v_lshlrev_b32_e32 v170, 16, v180
	v_and_b32_e32 v171, 0xffff0000, v180
	v_addc_co_u32_e32 v153, vcc, 0, v153, vcc
	v_pk_mul_f32 v[96:97], v[96:97], v[172:173]
	v_pk_mul_f32 v[64:65], v[64:65], v[170:171]
	flat_load_dwordx4 v[170:173], v[152:153] offset:2048
	v_lshlrev_b32_e32 v174, 16, v179
	v_and_b32_e32 v175, 0xffff0000, v179
	v_pk_mul_f32 v[70:71], v[70:71], v[174:175]
	v_lshlrev_b32_e32 v174, 16, v181
	v_and_b32_e32 v175, 0xffff0000, v181
	v_pk_mul_f32 v[66:67], v[66:67], v[174:175]
	flat_load_dwordx4 v[174:177], v[152:153] offset:2560
	v_lshlrev_b32_e32 v152, 16, v182
	v_and_b32_e32 v153, 0xffff0000, v182
	v_pk_mul_f32 v[60:61], v[60:61], v[152:153]
	v_lshlrev_b32_e32 v152, 16, v184
	v_and_b32_e32 v153, 0xffff0000, v184
	v_pk_mul_f32 v[56:57], v[56:57], v[152:153]
	v_lshlrev_b32_e32 v152, 16, v183
	v_and_b32_e32 v153, 0xffff0000, v183
	v_pk_mul_f32 v[62:63], v[62:63], v[152:153]
	v_lshlrev_b32_e32 v152, 16, v185
	v_and_b32_e32 v153, 0xffff0000, v185
	v_pk_mul_f32 v[58:59], v[58:59], v[152:153]
	s_waitcnt vmcnt(0) lgkmcnt(0)
	v_lshlrev_b32_e32 v152, 16, v136
	v_and_b32_e32 v153, 0xffff0000, v136
	v_lshlrev_b32_e32 v136, 16, v137
	v_and_b32_e32 v137, 0xffff0000, v137
	v_pk_mul_f32 v[54:55], v[54:55], v[136:137]
	v_lshlrev_b32_e32 v136, 16, v139
	v_and_b32_e32 v137, 0xffff0000, v139
	v_pk_mul_f32 v[50:51], v[50:51], v[136:137]
	v_lshlrev_b32_e32 v136, 16, v160
	v_and_b32_e32 v137, 0xffff0000, v160
	v_pk_mul_f32 v[44:45], v[44:45], v[136:137]
	v_lshlrev_b32_e32 v136, 16, v162
	v_and_b32_e32 v137, 0xffff0000, v162
	v_pk_mul_f32 v[40:41], v[40:41], v[136:137]
	v_lshlrev_b32_e32 v136, 16, v161
	v_and_b32_e32 v137, 0xffff0000, v161
	v_pk_mul_f32 v[46:47], v[46:47], v[136:137]
	v_lshlrev_b32_e32 v136, 16, v163
	v_and_b32_e32 v137, 0xffff0000, v163
	v_pk_mul_f32 v[42:43], v[42:43], v[136:137]
	v_pk_mul_f32 v[52:53], v[52:53], v[152:153]
	v_lshlrev_b32_e32 v136, 16, v132
	v_and_b32_e32 v137, 0xffff0000, v132
	v_lshlrev_b32_e32 v132, 16, v133
	v_and_b32_e32 v133, 0xffff0000, v133
	v_pk_mul_f32 v[38:39], v[38:39], v[132:133]
	v_lshlrev_b32_e32 v132, 16, v135
	v_and_b32_e32 v133, 0xffff0000, v135
	v_pk_mul_f32 v[34:35], v[34:35], v[132:133]
	v_lshlrev_b32_e32 v152, 16, v138
	v_and_b32_e32 v153, 0xffff0000, v138
	v_pk_mul_f32 v[36:37], v[36:37], v[136:137]
	v_lshlrev_b32_e32 v136, 16, v134
	v_and_b32_e32 v137, 0xffff0000, v134
	v_pk_mul_f32 v[48:49], v[48:49], v[152:153]
	v_lshlrev_b32_e32 v132, 16, v128
	v_and_b32_e32 v133, 0xffff0000, v128
	v_lshlrev_b32_e32 v128, 16, v129
	v_and_b32_e32 v129, 0xffff0000, v129
	v_pk_mul_f32 v[30:31], v[30:31], v[128:129]
	v_lshlrev_b32_e32 v128, 16, v131
	v_and_b32_e32 v129, 0xffff0000, v131
	v_pk_mul_f32 v[26:27], v[26:27], v[128:129]
	v_lshlrev_b32_e32 v128, 16, v166
	v_and_b32_e32 v129, 0xffff0000, v166
	v_pk_mul_f32 v[20:21], v[20:21], v[128:129]
	v_lshlrev_b32_e32 v128, 16, v168
	v_and_b32_e32 v129, 0xffff0000, v168
	v_pk_mul_f32 v[16:17], v[16:17], v[128:129]
	v_lshlrev_b32_e32 v128, 16, v167
	v_and_b32_e32 v129, 0xffff0000, v167
	v_pk_mul_f32 v[22:23], v[22:23], v[128:129]
	v_lshlrev_b32_e32 v128, 16, v169
	v_and_b32_e32 v129, 0xffff0000, v169
	v_pk_mul_f32 v[18:19], v[18:19], v[128:129]
	v_pk_mul_f32 v[28:29], v[28:29], v[132:133]
	v_lshlrev_b32_e32 v132, 16, v130
	v_and_b32_e32 v133, 0xffff0000, v130
	v_pk_mul_f32 v[32:33], v[32:33], v[136:137]
	v_lshlrev_b32_e32 v128, 16, v170
	v_and_b32_e32 v129, 0xffff0000, v170
	v_pk_mul_f32 v[12:13], v[12:13], v[128:129]
	v_lshlrev_b32_e32 v128, 16, v172
	v_and_b32_e32 v129, 0xffff0000, v172
	v_pk_mul_f32 v[8:9], v[8:9], v[128:129]
	v_lshlrev_b32_e32 v128, 16, v171
	v_and_b32_e32 v129, 0xffff0000, v171
	v_pk_mul_f32 v[14:15], v[14:15], v[128:129]
	v_lshlrev_b32_e32 v128, 16, v173
	v_and_b32_e32 v129, 0xffff0000, v173
	v_pk_mul_f32 v[10:11], v[10:11], v[128:129]
	v_lshlrev_b32_e32 v128, 16, v174
	v_and_b32_e32 v129, 0xffff0000, v174
	v_pk_mul_f32 v[4:5], v[4:5], v[128:129]
	v_lshlrev_b32_e32 v128, 16, v176
	v_and_b32_e32 v129, 0xffff0000, v176
	v_pk_mul_f32 v[0:1], v[0:1], v[128:129]
	v_lshlrev_b32_e32 v128, 16, v175
	v_and_b32_e32 v129, 0xffff0000, v175
	v_pk_mul_f32 v[6:7], v[6:7], v[128:129]
	v_lshlrev_b32_e32 v128, 16, v177
	v_and_b32_e32 v129, 0xffff0000, v177
	v_pk_mul_f32 v[24:25], v[24:25], v[132:133]
	v_pk_mul_f32 v[2:3], v[2:3], v[128:129]
	.p2align	6

.LBB0_559:
	s_cmp_lt_i32 s51, 1
	s_cbranch_scc1 .LBB0_570
	s_and_b64 s[64:65], s[52:53], exec
	s_cselect_b32 s59, s55, s61
	s_cselect_b32 s66, s54, s60
	s_cselect_b32 s67, s57, s63
	s_cselect_b32 s68, s56, s62
	s_add_i32 s69, s51, -2
	s_add_u32 vcc_lo, s62, 0x100
	s_addc_u32 vcc_hi, s63, 0
	s_add_u32 s60, s60, 0x80080
	v_mov_b32_e32 v0, 0
	s_addc_u32 s61, s61, 0
	s_mov_b32 s62, 0
	v_mov_b32_e32 v1, v0
	v_mov_b32_e32 v2, v0
	v_mov_b32_e32 v3, v0
	v_mov_b32_e32 v4, v0
	v_mov_b32_e32 v5, v0
	v_mov_b32_e32 v6, v0
	v_mov_b32_e32 v7, v0
	v_mov_b32_e32 v16, v0
	v_mov_b32_e32 v17, v0
	v_mov_b32_e32 v18, v0
	v_mov_b32_e32 v19, v0
	v_mov_b32_e32 v20, v0
	v_mov_b32_e32 v21, v0
	v_mov_b32_e32 v22, v0
	v_mov_b32_e32 v23, v0
	v_mov_b32_e32 v32, v0
	v_mov_b32_e32 v33, v0
	v_mov_b32_e32 v34, v0
	v_mov_b32_e32 v35, v0
	v_mov_b32_e32 v36, v0
	v_mov_b32_e32 v37, v0
	v_mov_b32_e32 v38, v0
	v_mov_b32_e32 v39, v0
	v_mov_b32_e32 v48, v0
	v_mov_b32_e32 v49, v0
	v_mov_b32_e32 v50, v0
	v_mov_b32_e32 v51, v0
	v_mov_b32_e32 v52, v0
	v_mov_b32_e32 v53, v0
	v_mov_b32_e32 v54, v0
	v_mov_b32_e32 v55, v0
	v_mov_b32_e32 v8, v0
	v_mov_b32_e32 v9, v0
	v_mov_b32_e32 v10, v0
	v_mov_b32_e32 v11, v0
	v_mov_b32_e32 v12, v0
	v_mov_b32_e32 v13, v0
	v_mov_b32_e32 v14, v0
	v_mov_b32_e32 v15, v0
	v_mov_b32_e32 v24, v0
	v_mov_b32_e32 v25, v0
	v_mov_b32_e32 v26, v0
	v_mov_b32_e32 v27, v0
	v_mov_b32_e32 v28, v0
	v_mov_b32_e32 v29, v0
	v_mov_b32_e32 v30, v0
	v_mov_b32_e32 v31, v0
	v_mov_b32_e32 v40, v0
	v_mov_b32_e32 v41, v0
	v_mov_b32_e32 v42, v0
	v_mov_b32_e32 v43, v0
	v_mov_b32_e32 v44, v0
	v_mov_b32_e32 v45, v0
	v_mov_b32_e32 v46, v0
	v_mov_b32_e32 v47, v0
	v_mov_b32_e32 v56, v0
	v_mov_b32_e32 v57, v0
	v_mov_b32_e32 v58, v0
	v_mov_b32_e32 v59, v0
	v_mov_b32_e32 v60, v0
	v_mov_b32_e32 v61, v0
	v_mov_b32_e32 v62, v0
	v_mov_b32_e32 v63, v0
	v_mov_b32_e32 v64, v0
	v_mov_b32_e32 v65, v0
	v_mov_b32_e32 v66, v0
	v_mov_b32_e32 v67, v0
	v_mov_b32_e32 v68, v0
	v_mov_b32_e32 v69, v0
	v_mov_b32_e32 v70, v0
	v_mov_b32_e32 v71, v0
	v_mov_b32_e32 v80, v0
	v_mov_b32_e32 v81, v0
	v_mov_b32_e32 v82, v0
	v_mov_b32_e32 v83, v0
	v_mov_b32_e32 v84, v0
	v_mov_b32_e32 v85, v0
	v_mov_b32_e32 v86, v0
	v_mov_b32_e32 v87, v0
	v_mov_b32_e32 v96, v0
	v_mov_b32_e32 v97, v0
	v_mov_b32_e32 v98, v0
	v_mov_b32_e32 v99, v0
	v_mov_b32_e32 v100, v0
	v_mov_b32_e32 v101, v0
	v_mov_b32_e32 v102, v0
	v_mov_b32_e32 v103, v0
	v_mov_b32_e32 v112, v0
	v_mov_b32_e32 v113, v0
	v_mov_b32_e32 v114, v0
	v_mov_b32_e32 v115, v0
	v_mov_b32_e32 v116, v0
	v_mov_b32_e32 v117, v0
	v_mov_b32_e32 v118, v0
	v_mov_b32_e32 v119, v0
	v_mov_b32_e32 v72, v0
	v_mov_b32_e32 v73, v0
	v_mov_b32_e32 v74, v0
	v_mov_b32_e32 v75, v0
	v_mov_b32_e32 v76, v0
	v_mov_b32_e32 v77, v0
	v_mov_b32_e32 v78, v0
	v_mov_b32_e32 v79, v0
	v_mov_b32_e32 v88, v0
	v_mov_b32_e32 v89, v0
	v_mov_b32_e32 v90, v0
	v_mov_b32_e32 v91, v0
	v_mov_b32_e32 v92, v0
	v_mov_b32_e32 v93, v0
	v_mov_b32_e32 v94, v0
	v_mov_b32_e32 v95, v0
	v_mov_b32_e32 v104, v0
	v_mov_b32_e32 v105, v0
	v_mov_b32_e32 v106, v0
	v_mov_b32_e32 v107, v0
	v_mov_b32_e32 v108, v0
	v_mov_b32_e32 v109, v0
	v_mov_b32_e32 v110, v0
	v_mov_b32_e32 v111, v0
	v_mov_b32_e32 v120, v0
	v_mov_b32_e32 v121, v0
	v_mov_b32_e32 v122, v0
	v_mov_b32_e32 v123, v0
	v_mov_b32_e32 v124, v0
	v_mov_b32_e32 v125, v0
	v_mov_b32_e32 v126, v0
	v_mov_b32_e32 v127, v0
	.p2align	6

.LBB0_728:
	s_cmp_lt_i32 s57, 1
	s_cbranch_scc1 .LBB0_739
	s_and_b64 s[40:41], s[50:51], exec
	s_cselect_b32 s59, s53, s61
	s_cselect_b32 s66, s52, s60
	s_cselect_b32 s67, s55, s63
	s_cselect_b32 s68, s54, s62
	s_add_i32 s69, s57, -2
	s_add_u32 s60, s60, 0x80080
	s_addc_u32 s61, s61, 0
	s_add_u32 s93, s62, 0x100
	v_mov_b32_e32 v0, 0
	s_addc_u32 s94, s63, 0
	s_mov_b32 s62, 0
	v_mov_b32_e32 v1, v0
	v_mov_b32_e32 v2, v0
	v_mov_b32_e32 v3, v0
	v_mov_b32_e32 v4, v0
	v_mov_b32_e32 v5, v0
	v_mov_b32_e32 v6, v0
	v_mov_b32_e32 v7, v0
	v_mov_b32_e32 v16, v0
	v_mov_b32_e32 v17, v0
	v_mov_b32_e32 v18, v0
	v_mov_b32_e32 v19, v0
	v_mov_b32_e32 v20, v0
	v_mov_b32_e32 v21, v0
	v_mov_b32_e32 v22, v0
	v_mov_b32_e32 v23, v0
	v_mov_b32_e32 v32, v0
	v_mov_b32_e32 v33, v0
	v_mov_b32_e32 v34, v0
	v_mov_b32_e32 v35, v0
	v_mov_b32_e32 v36, v0
	v_mov_b32_e32 v37, v0
	v_mov_b32_e32 v38, v0
	v_mov_b32_e32 v39, v0
	v_mov_b32_e32 v48, v0
	v_mov_b32_e32 v49, v0
	v_mov_b32_e32 v50, v0
	v_mov_b32_e32 v51, v0
	v_mov_b32_e32 v52, v0
	v_mov_b32_e32 v53, v0
	v_mov_b32_e32 v54, v0
	v_mov_b32_e32 v55, v0
	v_mov_b32_e32 v8, v0
	v_mov_b32_e32 v9, v0
	v_mov_b32_e32 v10, v0
	v_mov_b32_e32 v11, v0
	v_mov_b32_e32 v12, v0
	v_mov_b32_e32 v13, v0
	v_mov_b32_e32 v14, v0
	v_mov_b32_e32 v15, v0
	v_mov_b32_e32 v24, v0
	v_mov_b32_e32 v25, v0
	v_mov_b32_e32 v26, v0
	v_mov_b32_e32 v27, v0
	v_mov_b32_e32 v28, v0
	v_mov_b32_e32 v29, v0
	v_mov_b32_e32 v30, v0
	v_mov_b32_e32 v31, v0
	v_mov_b32_e32 v40, v0
	v_mov_b32_e32 v41, v0
	v_mov_b32_e32 v42, v0
	v_mov_b32_e32 v43, v0
	v_mov_b32_e32 v44, v0
	v_mov_b32_e32 v45, v0
	v_mov_b32_e32 v46, v0
	v_mov_b32_e32 v47, v0
	v_mov_b32_e32 v56, v0
	v_mov_b32_e32 v57, v0
	v_mov_b32_e32 v58, v0
	v_mov_b32_e32 v59, v0
	v_mov_b32_e32 v60, v0
	v_mov_b32_e32 v61, v0
	v_mov_b32_e32 v62, v0
	v_mov_b32_e32 v63, v0
	v_mov_b32_e32 v64, v0
	v_mov_b32_e32 v65, v0
	v_mov_b32_e32 v66, v0
	v_mov_b32_e32 v67, v0
	v_mov_b32_e32 v68, v0
	v_mov_b32_e32 v69, v0
	v_mov_b32_e32 v70, v0
	v_mov_b32_e32 v71, v0
	v_mov_b32_e32 v80, v0
	v_mov_b32_e32 v81, v0
	v_mov_b32_e32 v82, v0
	v_mov_b32_e32 v83, v0
	v_mov_b32_e32 v84, v0
	v_mov_b32_e32 v85, v0
	v_mov_b32_e32 v86, v0
	v_mov_b32_e32 v87, v0
	v_mov_b32_e32 v96, v0
	v_mov_b32_e32 v97, v0
	v_mov_b32_e32 v98, v0
	v_mov_b32_e32 v99, v0
	v_mov_b32_e32 v100, v0
	v_mov_b32_e32 v101, v0
	v_mov_b32_e32 v102, v0
	v_mov_b32_e32 v103, v0
	v_mov_b32_e32 v112, v0
	v_mov_b32_e32 v113, v0
	v_mov_b32_e32 v114, v0
	v_mov_b32_e32 v115, v0
	v_mov_b32_e32 v116, v0
	v_mov_b32_e32 v117, v0
	v_mov_b32_e32 v118, v0
	v_mov_b32_e32 v119, v0
	v_mov_b32_e32 v72, v0
	v_mov_b32_e32 v73, v0
	v_mov_b32_e32 v74, v0
	v_mov_b32_e32 v75, v0
	v_mov_b32_e32 v76, v0
	v_mov_b32_e32 v77, v0
	v_mov_b32_e32 v78, v0
	v_mov_b32_e32 v79, v0
	v_mov_b32_e32 v88, v0
	v_mov_b32_e32 v89, v0
	v_mov_b32_e32 v90, v0
	v_mov_b32_e32 v91, v0
	v_mov_b32_e32 v92, v0
	v_mov_b32_e32 v93, v0
	v_mov_b32_e32 v94, v0
	v_mov_b32_e32 v95, v0
	v_mov_b32_e32 v104, v0
	v_mov_b32_e32 v105, v0
	v_mov_b32_e32 v106, v0
	v_mov_b32_e32 v107, v0
	v_mov_b32_e32 v108, v0
	v_mov_b32_e32 v109, v0
	v_mov_b32_e32 v110, v0
	v_mov_b32_e32 v111, v0
	v_mov_b32_e32 v120, v0
	v_mov_b32_e32 v121, v0
	v_mov_b32_e32 v122, v0
	v_mov_b32_e32 v123, v0
	v_mov_b32_e32 v124, v0
	v_mov_b32_e32 v125, v0
	v_mov_b32_e32 v126, v0
	v_mov_b32_e32 v127, v0
	.p2align	6

.LBB0_831:
	s_mov_b32 s49, 4
	s_cmp_lt_i32 s49, 1
	s_cbranch_scc1 .LBB0_839
	s_and_b64 s[40:41], s[46:47], exec
	s_cselect_b32 s82, s15, s51
	s_cselect_b32 s83, s14, s50
	s_add_i32 s84, s49, -2
	s_add_u32 s85, s50, 0x100
	v_mov_b32_e32 v0, 0
	s_addc_u32 s86, s51, 0
	s_mov_b32 s54, 0
	s_mov_b64 s[50:51], 0
	v_mov_b32_e32 v1, v0
	v_mov_b32_e32 v2, v0
	v_mov_b32_e32 v3, v0
	v_mov_b32_e32 v4, v0
	v_mov_b32_e32 v5, v0
	v_mov_b32_e32 v6, v0
	v_mov_b32_e32 v7, v0
	v_mov_b32_e32 v16, v0
	v_mov_b32_e32 v17, v0
	v_mov_b32_e32 v18, v0
	v_mov_b32_e32 v19, v0
	v_mov_b32_e32 v20, v0
	v_mov_b32_e32 v21, v0
	v_mov_b32_e32 v22, v0
	v_mov_b32_e32 v23, v0
	v_mov_b32_e32 v32, v0
	v_mov_b32_e32 v33, v0
	v_mov_b32_e32 v34, v0
	v_mov_b32_e32 v35, v0
	v_mov_b32_e32 v36, v0
	v_mov_b32_e32 v37, v0
	v_mov_b32_e32 v38, v0
	v_mov_b32_e32 v39, v0
	v_mov_b32_e32 v48, v0
	v_mov_b32_e32 v49, v0
	v_mov_b32_e32 v50, v0
	v_mov_b32_e32 v51, v0
	v_mov_b32_e32 v52, v0
	v_mov_b32_e32 v53, v0
	v_mov_b32_e32 v54, v0
	v_mov_b32_e32 v55, v0
	v_mov_b32_e32 v8, v0
	v_mov_b32_e32 v9, v0
	v_mov_b32_e32 v10, v0
	v_mov_b32_e32 v11, v0
	v_mov_b32_e32 v12, v0
	v_mov_b32_e32 v13, v0
	v_mov_b32_e32 v14, v0
	v_mov_b32_e32 v15, v0
	v_mov_b32_e32 v24, v0
	v_mov_b32_e32 v25, v0
	v_mov_b32_e32 v26, v0
	v_mov_b32_e32 v27, v0
	v_mov_b32_e32 v28, v0
	v_mov_b32_e32 v29, v0
	v_mov_b32_e32 v30, v0
	v_mov_b32_e32 v31, v0
	v_mov_b32_e32 v40, v0
	v_mov_b32_e32 v41, v0
	v_mov_b32_e32 v42, v0
	v_mov_b32_e32 v43, v0
	v_mov_b32_e32 v44, v0
	v_mov_b32_e32 v45, v0
	v_mov_b32_e32 v46, v0
	v_mov_b32_e32 v47, v0
	v_mov_b32_e32 v56, v0
	v_mov_b32_e32 v57, v0
	v_mov_b32_e32 v58, v0
	v_mov_b32_e32 v59, v0
	v_mov_b32_e32 v60, v0
	v_mov_b32_e32 v61, v0
	v_mov_b32_e32 v62, v0
	v_mov_b32_e32 v63, v0
	v_mov_b32_e32 v64, v0
	v_mov_b32_e32 v65, v0
	v_mov_b32_e32 v66, v0
	v_mov_b32_e32 v67, v0
	v_mov_b32_e32 v68, v0
	v_mov_b32_e32 v69, v0
	v_mov_b32_e32 v70, v0
	v_mov_b32_e32 v71, v0
	v_mov_b32_e32 v80, v0
	v_mov_b32_e32 v81, v0
	v_mov_b32_e32 v82, v0
	v_mov_b32_e32 v83, v0
	v_mov_b32_e32 v84, v0
	v_mov_b32_e32 v85, v0
	v_mov_b32_e32 v86, v0
	v_mov_b32_e32 v87, v0
	v_mov_b32_e32 v96, v0
	v_mov_b32_e32 v97, v0
	v_mov_b32_e32 v98, v0
	v_mov_b32_e32 v99, v0
	v_mov_b32_e32 v100, v0
	v_mov_b32_e32 v101, v0
	v_mov_b32_e32 v102, v0
	v_mov_b32_e32 v103, v0
	v_mov_b32_e32 v112, v0
	v_mov_b32_e32 v113, v0
	v_mov_b32_e32 v114, v0
	v_mov_b32_e32 v115, v0
	v_mov_b32_e32 v116, v0
	v_mov_b32_e32 v117, v0
	v_mov_b32_e32 v118, v0
	v_mov_b32_e32 v119, v0
	v_mov_b32_e32 v72, v0
	v_mov_b32_e32 v73, v0
	v_mov_b32_e32 v74, v0
	v_mov_b32_e32 v75, v0
	v_mov_b32_e32 v76, v0
	v_mov_b32_e32 v77, v0
	v_mov_b32_e32 v78, v0
	v_mov_b32_e32 v79, v0
	v_mov_b32_e32 v88, v0
	v_mov_b32_e32 v89, v0
	v_mov_b32_e32 v90, v0
	v_mov_b32_e32 v91, v0
	v_mov_b32_e32 v92, v0
	v_mov_b32_e32 v93, v0
	v_mov_b32_e32 v94, v0
	v_mov_b32_e32 v95, v0
	v_mov_b32_e32 v104, v0
	v_mov_b32_e32 v105, v0
	v_mov_b32_e32 v106, v0
	v_mov_b32_e32 v107, v0
	v_mov_b32_e32 v108, v0
	v_mov_b32_e32 v109, v0
	v_mov_b32_e32 v110, v0
	v_mov_b32_e32 v111, v0
	v_mov_b32_e32 v120, v0
	v_mov_b32_e32 v121, v0
	v_mov_b32_e32 v122, v0
	v_mov_b32_e32 v123, v0
	v_mov_b32_e32 v124, v0
	v_mov_b32_e32 v125, v0
	v_mov_b32_e32 v126, v0
	v_mov_b32_e32 v127, v0
	.p2align	6

.LBB0_955:
	s_cmp_lt_i32 s47, 1
	s_cbranch_scc1 .LBB0_966
	s_and_b64 s[40:41], s[48:49], exec
	s_cselect_b32 s55, s51, s57
	s_cselect_b32 s62, s50, s56
	s_cselect_b32 s63, s53, s59
	s_cselect_b32 s64, s52, s58
	s_add_i32 s65, s47, -2
	s_add_u32 s95, s58, 0x100
	s_addc_u32 s96, s59, 0
	s_add_u32 s56, s56, 0x80080
	v_mov_b32_e32 v0, 0
	s_addc_u32 s57, s57, 0
	s_mov_b32 s58, 0
	v_mov_b32_e32 v1, v0
	v_mov_b32_e32 v2, v0
	v_mov_b32_e32 v3, v0
	v_mov_b32_e32 v4, v0
	v_mov_b32_e32 v5, v0
	v_mov_b32_e32 v6, v0
	v_mov_b32_e32 v7, v0
	v_mov_b32_e32 v16, v0
	v_mov_b32_e32 v17, v0
	v_mov_b32_e32 v18, v0
	v_mov_b32_e32 v19, v0
	v_mov_b32_e32 v20, v0
	v_mov_b32_e32 v21, v0
	v_mov_b32_e32 v22, v0
	v_mov_b32_e32 v23, v0
	v_mov_b32_e32 v32, v0
	v_mov_b32_e32 v33, v0
	v_mov_b32_e32 v34, v0
	v_mov_b32_e32 v35, v0
	v_mov_b32_e32 v36, v0
	v_mov_b32_e32 v37, v0
	v_mov_b32_e32 v38, v0
	v_mov_b32_e32 v39, v0
	v_mov_b32_e32 v48, v0
	v_mov_b32_e32 v49, v0
	v_mov_b32_e32 v50, v0
	v_mov_b32_e32 v51, v0
	v_mov_b32_e32 v52, v0
	v_mov_b32_e32 v53, v0
	v_mov_b32_e32 v54, v0
	v_mov_b32_e32 v55, v0
	v_mov_b32_e32 v8, v0
	v_mov_b32_e32 v9, v0
	v_mov_b32_e32 v10, v0
	v_mov_b32_e32 v11, v0
	v_mov_b32_e32 v12, v0
	v_mov_b32_e32 v13, v0
	v_mov_b32_e32 v14, v0
	v_mov_b32_e32 v15, v0
	v_mov_b32_e32 v24, v0
	v_mov_b32_e32 v25, v0
	v_mov_b32_e32 v26, v0
	v_mov_b32_e32 v27, v0
	v_mov_b32_e32 v28, v0
	v_mov_b32_e32 v29, v0
	v_mov_b32_e32 v30, v0
	v_mov_b32_e32 v31, v0
	v_mov_b32_e32 v40, v0
	v_mov_b32_e32 v41, v0
	v_mov_b32_e32 v42, v0
	v_mov_b32_e32 v43, v0
	v_mov_b32_e32 v44, v0
	v_mov_b32_e32 v45, v0
	v_mov_b32_e32 v46, v0
	v_mov_b32_e32 v47, v0
	v_mov_b32_e32 v56, v0
	v_mov_b32_e32 v57, v0
	v_mov_b32_e32 v58, v0
	v_mov_b32_e32 v59, v0
	v_mov_b32_e32 v60, v0
	v_mov_b32_e32 v61, v0
	v_mov_b32_e32 v62, v0
	v_mov_b32_e32 v63, v0
	v_mov_b32_e32 v64, v0
	v_mov_b32_e32 v65, v0
	v_mov_b32_e32 v66, v0
	v_mov_b32_e32 v67, v0
	v_mov_b32_e32 v68, v0
	v_mov_b32_e32 v69, v0
	v_mov_b32_e32 v70, v0
	v_mov_b32_e32 v71, v0
	v_mov_b32_e32 v80, v0
	v_mov_b32_e32 v81, v0
	v_mov_b32_e32 v82, v0
	v_mov_b32_e32 v83, v0
	v_mov_b32_e32 v84, v0
	v_mov_b32_e32 v85, v0
	v_mov_b32_e32 v86, v0
	v_mov_b32_e32 v87, v0
	v_mov_b32_e32 v96, v0
	v_mov_b32_e32 v97, v0
	v_mov_b32_e32 v98, v0
	v_mov_b32_e32 v99, v0
	v_mov_b32_e32 v100, v0
	v_mov_b32_e32 v101, v0
	v_mov_b32_e32 v102, v0
	v_mov_b32_e32 v103, v0
	v_mov_b32_e32 v112, v0
	v_mov_b32_e32 v113, v0
	v_mov_b32_e32 v114, v0
	v_mov_b32_e32 v115, v0
	v_mov_b32_e32 v116, v0
	v_mov_b32_e32 v117, v0
	v_mov_b32_e32 v118, v0
	v_mov_b32_e32 v119, v0
	v_mov_b32_e32 v72, v0
	v_mov_b32_e32 v73, v0
	v_mov_b32_e32 v74, v0
	v_mov_b32_e32 v75, v0
	v_mov_b32_e32 v76, v0
	v_mov_b32_e32 v77, v0
	v_mov_b32_e32 v78, v0
	v_mov_b32_e32 v79, v0
	v_mov_b32_e32 v88, v0
	v_mov_b32_e32 v89, v0
	v_mov_b32_e32 v90, v0
	v_mov_b32_e32 v91, v0
	v_mov_b32_e32 v92, v0
	v_mov_b32_e32 v93, v0
	v_mov_b32_e32 v94, v0
	v_mov_b32_e32 v95, v0
	v_mov_b32_e32 v104, v0
	v_mov_b32_e32 v105, v0
	v_mov_b32_e32 v106, v0
	v_mov_b32_e32 v107, v0
	v_mov_b32_e32 v108, v0
	v_mov_b32_e32 v109, v0
	v_mov_b32_e32 v110, v0
	v_mov_b32_e32 v111, v0
	v_mov_b32_e32 v120, v0
	v_mov_b32_e32 v121, v0
	v_mov_b32_e32 v122, v0
	v_mov_b32_e32 v123, v0
	v_mov_b32_e32 v124, v0
	v_mov_b32_e32 v125, v0
	v_mov_b32_e32 v126, v0
	v_mov_b32_e32 v127, v0
	.p2align	6

.LBB0_1102:
	s_mov_b32 s66, 32
	s_cmp_lt_i32 s66, 1
	s_cbranch_scc1 .LBB0_1098
	s_add_i32 s67, s66, -2
	s_add_u32 s46, s46, 0x80080
	s_addc_u32 s47, s47, 0
	s_add_u32 s68, s48, 0x100
	v_mov_b32_e32 v0, 0
	s_addc_u32 s69, s49, 0
	s_mov_b32 s48, 0
	v_mov_b32_e32 v1, v0
	v_mov_b32_e32 v2, v0
	v_mov_b32_e32 v3, v0
	v_mov_b32_e32 v4, v0
	v_mov_b32_e32 v5, v0
	v_mov_b32_e32 v6, v0
	v_mov_b32_e32 v7, v0
	v_mov_b32_e32 v16, v0
	v_mov_b32_e32 v17, v0
	v_mov_b32_e32 v18, v0
	v_mov_b32_e32 v19, v0
	v_mov_b32_e32 v20, v0
	v_mov_b32_e32 v21, v0
	v_mov_b32_e32 v22, v0
	v_mov_b32_e32 v23, v0
	v_mov_b32_e32 v32, v0
	v_mov_b32_e32 v33, v0
	v_mov_b32_e32 v34, v0
	v_mov_b32_e32 v35, v0
	v_mov_b32_e32 v36, v0
	v_mov_b32_e32 v37, v0
	v_mov_b32_e32 v38, v0
	v_mov_b32_e32 v39, v0
	v_mov_b32_e32 v48, v0
	v_mov_b32_e32 v49, v0
	v_mov_b32_e32 v50, v0
	v_mov_b32_e32 v51, v0
	v_mov_b32_e32 v52, v0
	v_mov_b32_e32 v53, v0
	v_mov_b32_e32 v54, v0
	v_mov_b32_e32 v55, v0
	v_mov_b32_e32 v8, v0
	v_mov_b32_e32 v9, v0
	v_mov_b32_e32 v10, v0
	v_mov_b32_e32 v11, v0
	v_mov_b32_e32 v12, v0
	v_mov_b32_e32 v13, v0
	v_mov_b32_e32 v14, v0
	v_mov_b32_e32 v15, v0
	v_mov_b32_e32 v24, v0
	v_mov_b32_e32 v25, v0
	v_mov_b32_e32 v26, v0
	v_mov_b32_e32 v27, v0
	v_mov_b32_e32 v28, v0
	v_mov_b32_e32 v29, v0
	v_mov_b32_e32 v30, v0
	v_mov_b32_e32 v31, v0
	v_mov_b32_e32 v40, v0
	v_mov_b32_e32 v41, v0
	v_mov_b32_e32 v42, v0
	v_mov_b32_e32 v43, v0
	v_mov_b32_e32 v44, v0
	v_mov_b32_e32 v45, v0
	v_mov_b32_e32 v46, v0
	v_mov_b32_e32 v47, v0
	v_mov_b32_e32 v56, v0
	v_mov_b32_e32 v57, v0
	v_mov_b32_e32 v58, v0
	v_mov_b32_e32 v59, v0
	v_mov_b32_e32 v60, v0
	v_mov_b32_e32 v61, v0
	v_mov_b32_e32 v62, v0
	v_mov_b32_e32 v63, v0
	v_mov_b32_e32 v64, v0
	v_mov_b32_e32 v65, v0
	v_mov_b32_e32 v66, v0
	v_mov_b32_e32 v67, v0
	v_mov_b32_e32 v68, v0
	v_mov_b32_e32 v69, v0
	v_mov_b32_e32 v70, v0
	v_mov_b32_e32 v71, v0
	v_mov_b32_e32 v80, v0
	v_mov_b32_e32 v81, v0
	v_mov_b32_e32 v82, v0
	v_mov_b32_e32 v83, v0
	v_mov_b32_e32 v84, v0
	v_mov_b32_e32 v85, v0
	v_mov_b32_e32 v86, v0
	v_mov_b32_e32 v87, v0
	v_mov_b32_e32 v96, v0
	v_mov_b32_e32 v97, v0
	v_mov_b32_e32 v98, v0
	v_mov_b32_e32 v99, v0
	v_mov_b32_e32 v100, v0
	v_mov_b32_e32 v101, v0
	v_mov_b32_e32 v102, v0
	v_mov_b32_e32 v103, v0
	v_mov_b32_e32 v112, v0
	v_mov_b32_e32 v113, v0
	v_mov_b32_e32 v114, v0
	v_mov_b32_e32 v115, v0
	v_mov_b32_e32 v116, v0
	v_mov_b32_e32 v117, v0
	v_mov_b32_e32 v118, v0
	v_mov_b32_e32 v119, v0
	v_mov_b32_e32 v72, v0
	v_mov_b32_e32 v73, v0
	v_mov_b32_e32 v74, v0
	v_mov_b32_e32 v75, v0
	v_mov_b32_e32 v76, v0
	v_mov_b32_e32 v77, v0
	v_mov_b32_e32 v78, v0
	v_mov_b32_e32 v79, v0
	v_mov_b32_e32 v88, v0
	v_mov_b32_e32 v89, v0
	v_mov_b32_e32 v90, v0
	v_mov_b32_e32 v91, v0
	v_mov_b32_e32 v92, v0
	v_mov_b32_e32 v93, v0
	v_mov_b32_e32 v94, v0
	v_mov_b32_e32 v95, v0
	v_mov_b32_e32 v104, v0
	v_mov_b32_e32 v105, v0
	v_mov_b32_e32 v106, v0
	v_mov_b32_e32 v107, v0
	v_mov_b32_e32 v108, v0
	v_mov_b32_e32 v109, v0
	v_mov_b32_e32 v110, v0
	v_mov_b32_e32 v111, v0
	v_mov_b32_e32 v120, v0
	v_mov_b32_e32 v121, v0
	v_mov_b32_e32 v122, v0
	v_mov_b32_e32 v123, v0
	v_mov_b32_e32 v124, v0
	v_mov_b32_e32 v125, v0
	v_mov_b32_e32 v126, v0
	v_mov_b32_e32 v127, v0
	.p2align	6

.LBB0_1220:
	s_cmp_lt_i32 s49, 1
	s_cbranch_scc1 .LBB0_1231
	s_and_b64 s[56:57], s[40:41], exec
	s_cselect_b32 s51, s45, s53
	s_cselect_b32 s58, s44, s52
	s_cselect_b32 s59, s47, s55
	s_cselect_b32 s60, s46, s54
	s_add_i32 s61, s49, -2
	s_add_u32 s86, s54, 0x100
	s_addc_u32 s87, s55, 0
	s_add_u32 s52, s52, 0x200080
	v_mov_b32_e32 v0, 0
	s_addc_u32 s53, s53, 0
	s_mov_b32 s54, 0
	v_mov_b32_e32 v1, v0
	v_mov_b32_e32 v2, v0
	v_mov_b32_e32 v3, v0
	v_mov_b32_e32 v4, v0
	v_mov_b32_e32 v5, v0
	v_mov_b32_e32 v6, v0
	v_mov_b32_e32 v7, v0
	v_mov_b32_e32 v16, v0
	v_mov_b32_e32 v17, v0
	v_mov_b32_e32 v18, v0
	v_mov_b32_e32 v19, v0
	v_mov_b32_e32 v20, v0
	v_mov_b32_e32 v21, v0
	v_mov_b32_e32 v22, v0
	v_mov_b32_e32 v23, v0
	v_mov_b32_e32 v32, v0
	v_mov_b32_e32 v33, v0
	v_mov_b32_e32 v34, v0
	v_mov_b32_e32 v35, v0
	v_mov_b32_e32 v36, v0
	v_mov_b32_e32 v37, v0
	v_mov_b32_e32 v38, v0
	v_mov_b32_e32 v39, v0
	v_mov_b32_e32 v48, v0
	v_mov_b32_e32 v49, v0
	v_mov_b32_e32 v50, v0
	v_mov_b32_e32 v51, v0
	v_mov_b32_e32 v52, v0
	v_mov_b32_e32 v53, v0
	v_mov_b32_e32 v54, v0
	v_mov_b32_e32 v55, v0
	v_mov_b32_e32 v8, v0
	v_mov_b32_e32 v9, v0
	v_mov_b32_e32 v10, v0
	v_mov_b32_e32 v11, v0
	v_mov_b32_e32 v12, v0
	v_mov_b32_e32 v13, v0
	v_mov_b32_e32 v14, v0
	v_mov_b32_e32 v15, v0
	v_mov_b32_e32 v24, v0
	v_mov_b32_e32 v25, v0
	v_mov_b32_e32 v26, v0
	v_mov_b32_e32 v27, v0
	v_mov_b32_e32 v28, v0
	v_mov_b32_e32 v29, v0
	v_mov_b32_e32 v30, v0
	v_mov_b32_e32 v31, v0
	v_mov_b32_e32 v40, v0
	v_mov_b32_e32 v41, v0
	v_mov_b32_e32 v42, v0
	v_mov_b32_e32 v43, v0
	v_mov_b32_e32 v44, v0
	v_mov_b32_e32 v45, v0
	v_mov_b32_e32 v46, v0
	v_mov_b32_e32 v47, v0
	v_mov_b32_e32 v56, v0
	v_mov_b32_e32 v57, v0
	v_mov_b32_e32 v58, v0
	v_mov_b32_e32 v59, v0
	v_mov_b32_e32 v60, v0
	v_mov_b32_e32 v61, v0
	v_mov_b32_e32 v62, v0
	v_mov_b32_e32 v63, v0
	v_mov_b32_e32 v64, v0
	v_mov_b32_e32 v65, v0
	v_mov_b32_e32 v66, v0
	v_mov_b32_e32 v67, v0
	v_mov_b32_e32 v68, v0
	v_mov_b32_e32 v69, v0
	v_mov_b32_e32 v70, v0
	v_mov_b32_e32 v71, v0
	v_mov_b32_e32 v80, v0
	v_mov_b32_e32 v81, v0
	v_mov_b32_e32 v82, v0
	v_mov_b32_e32 v83, v0
	v_mov_b32_e32 v84, v0
	v_mov_b32_e32 v85, v0
	v_mov_b32_e32 v86, v0
	v_mov_b32_e32 v87, v0
	v_mov_b32_e32 v96, v0
	v_mov_b32_e32 v97, v0
	v_mov_b32_e32 v98, v0
	v_mov_b32_e32 v99, v0
	v_mov_b32_e32 v100, v0
	v_mov_b32_e32 v101, v0
	v_mov_b32_e32 v102, v0
	v_mov_b32_e32 v103, v0
	v_mov_b32_e32 v112, v0
	v_mov_b32_e32 v113, v0
	v_mov_b32_e32 v114, v0
	v_mov_b32_e32 v115, v0
	v_mov_b32_e32 v116, v0
	v_mov_b32_e32 v117, v0
	v_mov_b32_e32 v118, v0
	v_mov_b32_e32 v119, v0
	v_mov_b32_e32 v72, v0
	v_mov_b32_e32 v73, v0
	v_mov_b32_e32 v74, v0
	v_mov_b32_e32 v75, v0
	v_mov_b32_e32 v76, v0
	v_mov_b32_e32 v77, v0
	v_mov_b32_e32 v78, v0
	v_mov_b32_e32 v79, v0
	v_mov_b32_e32 v88, v0
	v_mov_b32_e32 v89, v0
	v_mov_b32_e32 v90, v0
	v_mov_b32_e32 v91, v0
	v_mov_b32_e32 v92, v0
	v_mov_b32_e32 v93, v0
	v_mov_b32_e32 v94, v0
	v_mov_b32_e32 v95, v0
	v_mov_b32_e32 v104, v0
	v_mov_b32_e32 v105, v0
	v_mov_b32_e32 v106, v0
	v_mov_b32_e32 v107, v0
	v_mov_b32_e32 v108, v0
	v_mov_b32_e32 v109, v0
	v_mov_b32_e32 v110, v0
	v_mov_b32_e32 v111, v0
	v_mov_b32_e32 v120, v0
	v_mov_b32_e32 v121, v0
	v_mov_b32_e32 v122, v0
	v_mov_b32_e32 v123, v0
	v_mov_b32_e32 v124, v0
	v_mov_b32_e32 v125, v0
	v_mov_b32_e32 v126, v0
	v_mov_b32_e32 v127, v0
	.p2align	6
